# logical workgroup id permutation mode 2 (slot j -> (j&3)+4*(j>>3)+16*((j>>2)&1)): partial in-proj round on alternate groups of four hardware slots, per-slot role alternation kept
# speedup vs baseline: 1.0111x; 1.0111x over previous
; #define LAS __attribute__((address_space(3)))
; __global__ void __launch_bounds__(512, 2) fwd_megakernel(Args a) {
;     extern __shared__ __attribute__((aligned(16))) unsigned char lds_raw[];
;     LAS unsigned char* lds = (LAS unsigned char*)lds_raw;
;     cg::grid_group grid = cg::this_grid();
;     const int bid = blockIdx.x, G = gridDim.x;
;     if (threadIdx.x < 64) ((LAS unsigned*)(lds + 131072))[threadIdx.x] = 0u;
;     __syncthreads();
;     (void)xcd_barrier_post((unsigned*)(a.ws + WS_BAR), (volatile LAS unsigned*)(lds + 131072) + 8);
_Z14fwd_megakernel4Args:
	s_load_dwordx4 s[76:79], s[0:1], 0x80
	s_load_dwordx2 s[42:43], s[0:1], 0x90
	s_add_u32 s6, s0, 0x90
	v_and_b32_e32 v208, 0x3ff, v0
	s_mov_b32 s71, s2
	s_addc_u32 s7, s1, 0
	v_cmp_gt_u32_e32 vcc, 64, v208
	s_and_saveexec_b64 s[4:5], vcc
	v_lshl_add_u32 v1, v208, 2, 0
	v_add_u32_e32 v1, 0x20000, v1
	v_mov_b32_e32 v2, 0
	ds_write_b32 v1, v2
	s_or_b64 exec, exec, s[4:5]
	s_load_dword s2, s[0:1], 0x98
	s_waitcnt lgkmcnt(0)
	s_cmp_lg_u32 s42, 0x100
	s_cbranch_scc1 .Lperm_skip
	s_and_b32 s8, s71, 7
	s_lshr_b32 s9, s71, 3
	s_and_b32 s10, s9, 3
	s_bfe_u32 s11, s9, 0x10002
	s_lshr_b32 s9, s9, 3
	s_lshl_b32 s9, s9, 2
	s_lshl_b32 s11, s11, 4
	s_or_b32 s9, s9, s10
	s_or_b32 s9, s9, s11
	s_lshl_b32 s9, s9, 3
	s_or_b32 s71, s9, s8
